# store-burst de-phasing: half of each XCD's workgroups start the up GEMM ~6 us late so the two groups' write-through epilogue bursts do not coincide
# baseline (speedup 1.0000x reference)
; __global__ void __launch_bounds__(512, 2) fwd_megakernel(Ptrs Parg) {
;     ...
;         for (int half = 0; half < 2; ++half) {
;             if (PH(14)) { PHP; bf16_t* A2 = PJ; pg8::Gemm g{U, WupT, DM, DM, 0, 0, 0}; pg8::Sched S{64, 44, 1, G, bx, 64 * half, 64};
;               pg8::EpiStore<0> E{A2, 11264, 1};
;               pg8::gemm_phase<pg8::EpiStore<0>, pg8::Sched, GEMM_ALIGN, GEMM_SP2>(glds, g, S, E); }
.LBB0_1497:
	s_bitcmp1_b32 s2, 3
	s_cbranch_scc0 .Lstag_up_done
	s_sleep 100
	s_sleep 100
